# merge: cache-warming load (one per thread per K-iteration) for the next branch's first K-tile of both operands
# baseline (speedup 1.0000x reference)
; DI int tidx() { int t = threadIdx.x & 255; asm volatile("" : "+v"(t)); return t; }
; #define GEMM_STAGE(D_) do { unsigned char* d_ = (D_); \
;         *(u32x4*)(d_) = ra0; *(u32x4*)(d_ + OPB) = rb0; *(u32x4*)(d_ + PASSB) = ra1; *(u32x4*)(d_ + OPB + PASSB) = rb1; \
;         if constexpr (NJ == 4) { *(u32x4*)(d_ + 2 * PASSB) = ra2; *(u32x4*)(d_ + OPB + 2 * PASSB) = rb2; *(u32x4*)(d_ + 3 * PASSB) = ra3; *(u32x4*)(d_ + OPB + 3 * PASSB) = rb3; } } while (0)
; template <int BK>
; DI void gemm_mainloop(const bf16_t* A, int lda, const bf16_t* B, int ldb, int K, f32x16 (&acc)[2][2], unsigned char* smem) {
;     ...
;     const int tid = tidx(), lane = tid & 63, w = tid >> 6, wm = w >> 1, wn = w & 1, r = lane & 31, hh = lane >> 5;
;     const int lrow = tid / CPR, lcol = (tid % CPR) * 8;
;     const bf16_t* ap = A + (size_t)lrow * lda + lcol;
;     const bf16_t* bp = B + (size_t)lrow * ldb + lcol;
;     const size_t astep = (size_t)RPP * lda, bstep = (size_t)RPP * ldb;
;     const int st_off = lrow * ROWB + (tid % CPR) * 16;
;     u32x4 ra0, ra1, ra2, ra3, rb0, rb1, rb2, rb3;
;     ra0 = *(const u32x4*)(ap); rb0 = *(const u32x4*)(bp);
;     ra1 = *(const u32x4*)(ap + astep); rb1 = *(const u32x4*)(bp + bstep);
;     if constexpr (NJ == 4) { ra2 = *(const u32x4*)(ap + 2 * astep); rb2 = *(const u32x4*)(bp + 2 * bstep); ra3 = *(const u32x4*)(ap + 3 * astep); rb3 = *(const u32x4*)(bp + 3 * bstep); }
;     else { ra2 = ra0; ra3 = ra0; rb2 = rb0; rb3 = rb0; }
;     ...
;     GEMM_STAGE(smem + st_off);
;     __syncthreads();
; DI void phase_merge(KargPtr p, int l, unsigned char* smem) {
;     ...
;         for (int br = 0; br < 3; ++br) {
;             f32x16 acc[2][2]; zero_acc(acc);
;             const bf16_t* Y = (br == 0 ? p->qf : br == 1 ? p->qn : p->qs) + (size_t)m0 * 512;
;             const bf16_t* WO = WL + (br == 0 ? W_OF : br == 1 ? W_OM : W_OS) + (size_t)nt * 128 * 512;
;             gemm_mainloop<64>(WO, 512, Y, 512, 512, acc, smem);
;             const bf16_t* G = (br == 0 ? p->gs0 : p->gs1 + (size_t)(br - 1) * T_TOK * 1024) + (size_t)(m0 + wn * 64 + r) * 1024 + nt * 128 + wm * 64 + 4 * hh;
;             u32x2 gv[2][2][4];
; #pragma unroll
;             for (int a = 0; a < 2; ++a)
; #pragma unroll
;                 for (int c = 0; c < 2; ++c)
; #pragma unroll
;                     for (int g = 0; g < 4; ++g) gv[a][c][g] = *(const u32x2*)(G + (size_t)c * 32 * 1024 + a * 32 + 8 * g);
.LBB0_555:
	s_cmp_lg_u32 s5, 0
	s_cselect_b64 s[12:13], -1, 0
	s_cmp_eq_u32 s5, 1
	s_movk_i32 s14, 0x128
	s_mov_b32 s15, 0x7e8000
	s_cselect_b32 s14, s14, 0xf8
	s_cselect_b32 s15, s15, 0x868000
	s_cmp_eq_u32 s5, 0
	s_cselect_b32 s14, 0xe0, s14
	s_cselect_b32 s19, 0x768000, s15
	s_add_u32 s14, s0, s14
	s_addc_u32 s15, s1, 0
	s_load_dwordx2 s[14:15], s[14:15], 0x0
	s_cmp_eq_u32 s5, 0
	s_movk_i32 s24, 0x170
	s_cselect_b32 s24, 0x168, s24
	s_add_u32 s24, s0, s24
	s_addc_u32 s25, s1, 0
	s_load_dwordx2 s[22:23], s[24:25], 0x0
	s_add_i32 s24, s5, -1
	s_max_i32 s24, s24, 0
	s_mov_b32 s25, 0
	s_lshl_b64 s[24:25], s[24:25], 26
	s_cmp_eq_u32 s5, 0
	s_movk_i32 s34, 0xf8
	s_cselect_b32 s34, 0x128, s34
	s_mov_b32 s35, 0x868000
	s_cselect_b32 s35, 0x7e8000, s35
	s_lshl_b32 s35, s35, 1
	s_add_u32 s28, s0, s34
	s_addc_u32 s29, s1, 0
	s_load_dwordx2 s[28:29], s[28:29], 0x0
	s_add_u32 s34, s17, s35
	s_addc_u32 s35, s18, 0
	v_mov_b32_e32 v48, v199
	v_mov_b32_e32 v10, v167
	v_ashrrev_i32_e32 v4, 31, v48
	v_lshrrev_b32_e32 v4, 29, v4
	v_add_u32_e32 v4, v48, v4
	s_waitcnt lgkmcnt(0)
	s_add_u32 s14, s14, s10
	v_ashrrev_i32_e32 v46, 3, v4
	v_and_b32_e32 v4, -8, v4
	s_addc_u32 s15, s15, s11
	s_lshl_b32 s19, s19, 1
	v_sub_u32_e32 v49, v48, v4
	s_add_u32 s20, s17, s19
	v_lshlrev_b32_e32 v4, 3, v49
	v_ashrrev_i32_e32 v47, 31, v46
	s_addc_u32 s21, s18, 0
	s_add_u32 s22, s22, s24
	s_addc_u32 s23, s23, s25
	s_add_u32 s28, s28, s10
	s_addc_u32 s29, s29, s11
	v_lshlrev_b64 v[6:7], 10, v[46:47]
	v_ashrrev_i32_e32 v5, 31, v4
	v_lshl_add_u64 v[8:9], s[20:21], 0, v[6:7]
	v_lshlrev_b64 v[4:5], 1, v[4:5]
	v_lshl_add_u64 v[134:135], v[8:9], 0, v[4:5]
	v_lshl_add_u64 v[6:7], s[14:15], 0, v[6:7]
	v_lshl_add_u64 v[136:137], v[6:7], 0, v[4:5]
	v_add_co_u32_e32 v4, vcc, s69, v134
	global_load_dwordx4 v[14:17], v[134:135], off
	global_load_dwordx4 v[18:21], v[136:137], off
	v_addc_co_u32_e32 v5, vcc, 0, v135, vcc
	global_load_dwordx4 v[22:25], v[4:5], off
	v_add_co_u32_e32 v4, vcc, s69, v136
	v_and_b32_e32 v47, 31, v48
	s_nop 0
	v_addc_co_u32_e32 v5, vcc, 0, v137, vcc
	global_load_dwordx4 v[26:29], v[4:5], off
	v_add_co_u32_e32 v4, vcc, s65, v134
	v_lshrrev_b32_e32 v50, 1, v48
	s_nop 0
	v_addc_co_u32_e32 v5, vcc, 0, v135, vcc
	global_load_dwordx4 v[30:33], v[4:5], off
	v_add_co_u32_e32 v4, vcc, s65, v136
	s_mov_b32 s20, 0xfffffc0
	s_nop 0
	v_addc_co_u32_e32 v5, vcc, 0, v137, vcc
	global_load_dwordx4 v[34:37], v[4:5], off
	v_add_co_u32_e32 v4, vcc, s67, v136
	v_and_b32_e32 v51, 0x5f, v48
	s_nop 0
	v_addc_co_u32_e32 v5, vcc, 0, v137, vcc
	global_load_dwordx4 v[38:41], v[4:5], off
	v_add_co_u32_e32 v4, vcc, s67, v134
	v_and_or_b32 v47, v50, s20, v47
	s_nop 0
	v_addc_co_u32_e32 v5, vcc, 0, v135, vcc
	global_load_dwordx4 v[42:45], v[4:5], off
	v_lshl_add_u64 v[196:197], s[22:23], 0, v[132:133]
	v_lshl_add_u64 v[196:197], s[8:9], 1, v[196:197]
	v_lshl_add_u64 v[196:197], v[0:1], 1, v[196:197]
	v_lshl_add_u64 v[196:197], v[196:197], 0, v[2:3]
	v_add_co_u32_e32 v208, vcc, 0x10000, v196
	s_nop 1
	v_addc_co_u32_e32 v209, vcc, 0, v197, vcc
	global_load_dwordx2 v[222:223], v[196:197], off
	global_load_dwordx2 v[224:225], v[196:197], off offset:16
	global_load_dwordx2 v[226:227], v[196:197], off offset:32
	global_load_dwordx2 v[228:229], v[196:197], off offset:48
	global_load_dwordx2 v[230:231], v[208:209], off
	global_load_dwordx2 v[232:233], v[208:209], off offset:16
	global_load_dwordx2 v[234:235], v[208:209], off offset:32
	global_load_dwordx2 v[236:237], v[208:209], off offset:48
	global_load_dwordx2 v[238:239], v[196:197], off offset:64
	global_load_dwordx2 v[240:241], v[196:197], off offset:80
	global_load_dwordx2 v[242:243], v[196:197], off offset:96
	global_load_dwordx2 v[244:245], v[196:197], off offset:112
	global_load_dwordx2 v[246:247], v[208:209], off offset:64
	global_load_dwordx2 v[248:249], v[208:209], off offset:80
	global_load_dwordx2 v[250:251], v[208:209], off offset:96
	global_load_dwordx2 v[252:253], v[208:209], off offset:112
	v_and_b32_e32 v196, 0x7f, v199
	v_lshlrev_b32_e32 v196, 10, v196
	v_mov_b32_e32 v197, 0
	v_cmp_gt_u32_e32 vcc, 0x80, v199
	v_mov_b32_e32 v208, s34
	v_mov_b32_e32 v209, s35
	v_mov_b32_e32 v138, s28
	v_mov_b32_e32 v139, s29
	v_cndmask_b32_e32 v208, v208, v138, vcc
	v_cndmask_b32_e32 v209, v209, v139, vcc
	v_lshl_add_u64 v[196:197], v[208:209], 0, v[196:197]
	v_and_b32_e32 v48, 16, v50
	v_mad_u64_u32 v[154:155], s[20:21], v47, s74, v[48:49]
	v_mul_lo_u32 v46, v46, s74
	v_lshlrev_b32_e32 v47, 4, v49
	v_add3_u32 v156, s3, v46, v47
	s_mov_b64 s[14:15], 0
	s_mov_b32 s19, 0
	v_mov_b32_e32 v4, 0
	v_mov_b32_e32 v5, v167
	v_mov_b32_e32 v6, v167
	v_mov_b32_e32 v7, v167
	v_mov_b32_e32 v8, v167
	v_mov_b32_e32 v9, v167
	v_mov_b32_e32 v11, v167
	v_mov_b32_e32 v12, v167
	v_mov_b32_e32 v13, v167
	v_mad_u32_u24 v155, v51, s74, v48
	v_mov_b32_e32 v46, v167
	v_mov_b32_e32 v47, v167
	v_mov_b32_e32 v48, v167
	v_mov_b32_e32 v49, v167
	v_mov_b32_e32 v50, v167
	v_mov_b32_e32 v51, v167
	v_mov_b32_e32 v52, 0
	v_mov_b32_e32 v53, v167
	v_mov_b32_e32 v54, v167
	v_mov_b32_e32 v55, v167
	v_mov_b32_e32 v56, v167
	v_mov_b32_e32 v57, v167
	v_mov_b32_e32 v58, v167
	s_waitcnt vmcnt(22)
	ds_write_b128 v156, v[18:21] offset:18432
	ds_write_b128 v156, v[14:17]
	s_waitcnt vmcnt(20)
	ds_write_b128 v156, v[26:29] offset:23040
	s_waitcnt vmcnt(18)
	ds_write_b128 v156, v[34:37] offset:27648
	s_waitcnt vmcnt(17)
	ds_write_b128 v156, v[38:41] offset:32256
	ds_write_b128 v156, v[22:25] offset:4608
	ds_write_b128 v156, v[30:33] offset:9216
	s_waitcnt vmcnt(16)
	ds_write_b128 v156, v[42:45] offset:13824
	v_mov_b32_e32 v14, v167
	v_mov_b32_e32 v15, v167
	v_mov_b32_e32 v16, v167
	v_mov_b32_e32 v17, v167
	v_mov_b32_e32 v18, v167
	v_mov_b32_e32 v19, v167
	v_mov_b32_e32 v20, 0
	v_mov_b32_e32 v21, v167
	v_mov_b32_e32 v22, v167
	v_mov_b32_e32 v23, v167
	v_mov_b32_e32 v24, v167
	v_mov_b32_e32 v25, v167
	v_mov_b32_e32 v26, v167
	v_mov_b32_e32 v27, v167
	v_mov_b32_e32 v28, v167
	v_mov_b32_e32 v29, v167
	v_mov_b32_e32 v30, v167
	v_mov_b32_e32 v31, v167
	v_mov_b32_e32 v32, v167
	v_mov_b32_e32 v33, v167
	v_mov_b32_e32 v34, v167
	v_mov_b32_e32 v35, v167
	v_mov_b32_e32 v36, 0
	v_mov_b32_e32 v37, v167
	v_mov_b32_e32 v38, v167
	v_mov_b32_e32 v39, v167
	v_mov_b32_e32 v40, v167
	v_mov_b32_e32 v41, v167
	v_mov_b32_e32 v42, v167
	v_mov_b32_e32 v43, v167
	v_mov_b32_e32 v44, v167
	v_mov_b32_e32 v45, v167
	v_mov_b32_e32 v59, v167
	v_mov_b32_e32 v60, v167
	v_mov_b32_e32 v61, v167
	v_mov_b32_e32 v62, v167
	v_mov_b32_e32 v63, v167
	v_mov_b32_e32 v64, v167
	v_mov_b32_e32 v65, v167
	v_mov_b32_e32 v66, v167
	v_mov_b32_e32 v67, v167
	s_waitcnt lgkmcnt(0)
	s_barrier
; #define GLOAD16(dst, ptr) asm volatile("global_load_dwordx4 %0, %1, off" : "=v"(dst) : "v"(ptr))
; #define GEMM_STAGE(D_) do { unsigned char* d_ = (D_); \
;         *(u32x4*)(d_) = ra0; *(u32x4*)(d_ + OPB) = rb0; *(u32x4*)(d_ + PASSB) = ra1; *(u32x4*)(d_ + OPB + PASSB) = rb1; \
;         if constexpr (NJ == 4) { *(u32x4*)(d_ + 2 * PASSB) = ra2; *(u32x4*)(d_ + OPB + 2 * PASSB) = rb2; *(u32x4*)(d_ + 3 * PASSB) = ra3; *(u32x4*)(d_ + OPB + 3 * PASSB) = rb3; } } while (0)
; template <int BK>
; DI void gemm_mainloop(const bf16_t* A, int lda, const bf16_t* B, int ldb, int K, f32x16 (&acc)[2][2], unsigned char* smem) {
;     ...
;     for (int kt = 0; kt < nk - 1; ++kt) {
;         const int buf = kt & 1;
;         ap += BK; bp += BK;
;         GLOAD16(ra0, ap); GLOAD16(rb0, bp); GLOAD16(ra1, ap + astep); GLOAD16(rb1, bp + bstep);
;         if constexpr (NJ == 4) { GLOAD16(ra2, ap + 2 * astep); GLOAD16(rb2, bp + 2 * bstep); GLOAD16(ra3, ap + 3 * astep); GLOAD16(rb3, bp + 3 * bstep); }
;         __builtin_amdgcn_sched_barrier(0);
;         GEMM_COMPUTE(buf);
;         __builtin_amdgcn_sched_barrier(0);
;         if constexpr (NJ == 4) asm volatile("s_waitcnt vmcnt(0)" : "+v"(ra0), "+v"(rb0), "+v"(ra1), "+v"(rb1), "+v"(ra2), "+v"(rb2), "+v"(ra3), "+v"(rb3));
;         else asm volatile("s_waitcnt vmcnt(0)" : "+v"(ra0), "+v"(rb0), "+v"(ra1), "+v"(rb1));
;         GEMM_STAGE(smem + (buf ^ 1) * STB + st_off);
;         __syncthreads();
;     }
;     GEMM_COMPUTE((nk - 1) & 1);
;     __syncthreads();
.LBB0_556:
	v_lshl_add_u64 v[146:147], v[134:135], 0, s[14:15]
	v_lshl_add_u64 v[148:149], v[136:137], 0, s[14:15]
	v_lshl_add_u64 v[138:139], v[146:147], 0, s[92:93]
	v_lshl_add_u64 v[142:143], v[148:149], 0, s[92:93]
	v_lshl_add_u64 v[150:151], v[146:147], 0, s[80:81]
	v_lshl_add_u64 v[158:159], v[148:149], 0, s[80:81]
	v_lshl_add_u64 v[162:163], v[146:147], 0, s[40:41]
	v_lshl_add_u64 v[168:169], v[148:149], 0, s[40:41]
	v_lshl_add_u64 v[146:147], v[146:147], 0, s[94:95]
	s_and_b32 s20, s19, 1
	global_load_dwordx4 v[138:141], v[138:139], off
	global_load_dwordx4 v[142:145], v[142:143], off
	global_load_dwordx4 v[150:153], v[150:151], off
	global_load_dwordx4 v[158:161], v[158:159], off
	global_load_dwordx4 v[162:165], v[162:163], off
	global_load_dwordx4 v[168:171], v[168:169], off
	global_load_dwordx4 v[172:175], v[146:147], off
	v_lshl_add_u64 v[146:147], v[148:149], 0, s[94:95]
	global_load_dwordx4 v[176:179], v[146:147], off
	global_load_dword v208, v[196:197], off
	s_mul_i32 s21, s20, 0x9000
	s_add_i32 s21, s3, s21
	v_add_u32_e32 v146, s21, v154
	v_add_u32_e32 v147, s21, v155
	ds_read_b128 v[180:183], v146
	ds_read_b128 v[184:187], v146 offset:32
	ds_read_b128 v[188:191], v146 offset:4608
	ds_read_b128 v[192:195], v146 offset:4640
	ds_read_b128 v[200:203], v147 offset:18432
	ds_read_b128 v[210:213], v147 offset:18464
	ds_read_b128 v[214:217], v147 offset:23040
	ds_read_b128 v[218:221], v147 offset:23072
	s_waitcnt lgkmcnt(3)
	v_mfma_f32_32x32x16_bf16 v[52:67], v[180:183], v[200:203], v[52:67]
	s_waitcnt lgkmcnt(1)
	v_mfma_f32_32x32x16_bf16 v[36:51], v[180:183], v[214:217], v[36:51]
	v_mfma_f32_32x32x16_bf16 v[20:35], v[188:191], v[200:203], v[20:35]
	v_mfma_f32_32x32x16_bf16 v[4:19], v[188:191], v[214:217], v[4:19]
	ds_read_b128 v[180:183], v146 offset:64
	ds_read_b128 v[188:191], v146 offset:4672
	ds_read_b128 v[200:203], v147 offset:18496
	ds_read_b128 v[214:217], v147 offset:23104
	v_mfma_f32_32x32x16_bf16 v[52:67], v[184:187], v[210:213], v[52:67]
	s_waitcnt lgkmcnt(4)
	v_mfma_f32_32x32x16_bf16 v[36:51], v[184:187], v[218:221], v[36:51]
	v_mfma_f32_32x32x16_bf16 v[20:35], v[192:195], v[210:213], v[20:35]
	v_mfma_f32_32x32x16_bf16 v[4:19], v[192:195], v[218:221], v[4:19]
	ds_read_b128 v[184:187], v146 offset:96
	ds_read_b128 v[192:195], v146 offset:4704
	ds_read_b128 v[210:213], v147 offset:18528
	ds_read_b128 v[218:221], v147 offset:23136
	s_waitcnt lgkmcnt(5)
	v_mfma_f32_32x32x16_bf16 v[52:67], v[180:183], v[200:203], v[52:67]
	s_waitcnt lgkmcnt(4)
	v_mfma_f32_32x32x16_bf16 v[36:51], v[180:183], v[214:217], v[36:51]
	v_mfma_f32_32x32x16_bf16 v[20:35], v[188:191], v[200:203], v[20:35]
	v_mfma_f32_32x32x16_bf16 v[4:19], v[188:191], v[214:217], v[4:19]
	s_waitcnt lgkmcnt(1)
	v_mfma_f32_32x32x16_bf16 v[52:67], v[184:187], v[210:213], v[52:67]
	s_waitcnt lgkmcnt(0)
	v_mfma_f32_32x32x16_bf16 v[36:51], v[184:187], v[218:221], v[36:51]
	v_mfma_f32_32x32x16_bf16 v[20:35], v[192:195], v[210:213], v[20:35]
	v_mfma_f32_32x32x16_bf16 v[4:19], v[192:195], v[218:221], v[4:19]
	s_xor_b32 s20, s20, 1
	s_add_i32 s19, s19, 1
	s_add_u32 s14, s14, 0x80
	s_mul_i32 s20, s20, 0x9000
	s_addc_u32 s15, s15, 0
	s_barrier
	s_waitcnt vmcnt(0)
	v_add_u32_e32 v146, s20, v156
	s_cmpk_lg_i32 s14, 0x380
	ds_write_b128 v146, v[138:141]
	ds_write_b128 v146, v[142:145] offset:18432
	ds_write_b128 v146, v[150:153] offset:4608
	ds_write_b128 v146, v[158:161] offset:23040
	ds_write_b128 v146, v[162:165] offset:9216
	ds_write_b128 v146, v[168:171] offset:27648
	ds_write_b128 v146, v[172:175] offset:13824
	ds_write_b128 v146, v[176:179] offset:32256
	s_waitcnt lgkmcnt(0)
	s_barrier
	s_cbranch_scc1 .LBB0_556
	v_add_u32_e32 v146, s3, v154
	v_add_u32_e32 v147, s3, v155
	ds_read_b128 v[134:137], v146 offset:36864
	ds_read_b128 v[138:141], v146 offset:36896
	ds_read_b128 v[142:145], v146 offset:41472
	ds_read_b128 v[150:153], v146 offset:41504
	ds_read_b128 v[154:157], v147 offset:55296
	ds_read_b128 v[158:161], v147 offset:55328
	ds_read_b128 v[162:165], v147 offset:59904
	ds_read_b128 v[168:171], v147 offset:59936
	s_waitcnt lgkmcnt(3)
	v_mfma_f32_32x32x16_bf16 v[52:67], v[134:137], v[154:157], v[52:67]
	s_waitcnt lgkmcnt(1)
	v_mfma_f32_32x32x16_bf16 v[36:51], v[134:137], v[162:165], v[36:51]
	v_mfma_f32_32x32x16_bf16 v[20:35], v[142:145], v[154:157], v[20:35]
	v_mfma_f32_32x32x16_bf16 v[4:19], v[142:145], v[162:165], v[4:19]
	ds_read_b128 v[134:137], v146 offset:36928
	ds_read_b128 v[142:145], v146 offset:41536
	ds_read_b128 v[154:157], v147 offset:55360
	ds_read_b128 v[162:165], v147 offset:59968
	v_mfma_f32_32x32x16_bf16 v[52:67], v[138:141], v[158:161], v[52:67]
	s_waitcnt lgkmcnt(4)
	v_mfma_f32_32x32x16_bf16 v[36:51], v[138:141], v[168:171], v[36:51]
	v_mfma_f32_32x32x16_bf16 v[20:35], v[150:153], v[158:161], v[20:35]
	v_mfma_f32_32x32x16_bf16 v[4:19], v[150:153], v[168:171], v[4:19]
	ds_read_b128 v[138:141], v146 offset:36960
	ds_read_b128 v[150:153], v146 offset:41568
	ds_read_b128 v[158:161], v147 offset:55392
	ds_read_b128 v[168:171], v147 offset:60000
	s_waitcnt lgkmcnt(5)
	v_mfma_f32_32x32x16_bf16 v[52:67], v[134:137], v[154:157], v[52:67]
	s_waitcnt lgkmcnt(4)
	v_mfma_f32_32x32x16_bf16 v[36:51], v[134:137], v[162:165], v[36:51]
	v_mfma_f32_32x32x16_bf16 v[20:35], v[142:145], v[154:157], v[20:35]
	v_mfma_f32_32x32x16_bf16 v[4:19], v[142:145], v[162:165], v[4:19]
	s_waitcnt lgkmcnt(1)
	v_mfma_f32_32x32x16_bf16 v[52:67], v[138:141], v[158:161], v[52:67]
	s_mov_b64 s[14:15], -1
	s_and_b64 vcc, exec, s[12:13]
	s_waitcnt lgkmcnt(0)
	s_barrier
	v_mfma_f32_32x32x16_bf16 v[36:51], v[138:141], v[168:171], v[36:51]
	v_mfma_f32_32x32x16_bf16 v[20:35], v[150:153], v[158:161], v[20:35]
	v_mfma_f32_32x32x16_bf16 v[4:19], v[150:153], v[168:171], v[4:19]
	s_cbranch_vccz .LBB0_559
	s_load_dwordx2 s[12:13], s[0:1], 0x170
	s_add_i32 s84, s5, -1
	s_lshl_b64 s[14:15], s[84:85], 26
	s_waitcnt lgkmcnt(0)
	s_add_u32 s12, s12, s14
	s_addc_u32 s13, s13, s15
	s_mov_b64 s[14:15], 0
